# hand-written SEC1/SEC2 bodies now use the per-tile hoisted rs registers (no own loads/drain)
# baseline (speedup 1.0000x reference)
.LBB0_154:
	s_andn2_b64 vcc, exec, s[0:1]
	s_cbranch_vccnz .LBB0_157
	s_lshl_b32 s0, s31, 7
	s_lshl_b32 s3, s49, 6
	s_add_i32 s0, s0, s3
	s_add_i32 s0, s0, 0x20d40
	v_bfe_u32 v145, v213, 4, 2
	v_lshlrev_b32_e32 v146, 4, v145
	v_and_b32_e32 v147, 8, v181
	v_lshlrev_b32_e32 v147, 2, v147
	v_xor_b32_e32 v146, v146, v147
	v_lshl_add_u32 v140, v181, 6, v146
	v_add_u32_e32 v140, s0, v140
	v_bfe_u32 v146, v213, 2, 2
	v_lshl_add_u32 v146, v145, 3, v146
	v_lshlrev_b32_e32 v146, 6, v146
	v_and_b32_e32 v147, 1, v145
	v_lshl_add_u32 v146, v147, 5, v146
	v_and_b32_e32 v147, 3, v213
	v_lshl_add_u32 v146, v147, 3, v146
	v_add_u32_e32 v141, s0, v146
	v_xor_b32_e32 v146, 32, v146
	v_add_u32_e32 v142, s0, v146
	v_add_u32_e32 v168, s49, v181
	v_mul_u32_u24_e32 v168, 0x1100, v168
	v_readlane_b32 s4, v255, 20
	v_readlane_b32 s5, v255, 21
	s_lshr_b32 s3, s74, 7
	s_add_i32 s3, s3, -8
	s_cmp_eq_u32 s48, 64
	s_cbranch_scc1 .Lsec2_a_meta
	v_lshl_add_u32 v143, v145, 4, v168
	s_lshr_b32 s17, s48, 3
	s_lshl_b32 s17, s17, 3
	s_add_i32 s17, s17, s3
	s_mul_i32 s17, s17, 0x88000
	s_and_b32 vcc_lo, s48, 7
	s_lshl_b32 vcc_lo, vcc_lo, 9
	s_lshl_b32 vcc_hi, s31, 1
	s_add_i32 vcc_lo, vcc_lo, vcc_hi
	s_addk_i32 vcc_lo, 0x100
	s_add_i32 s17, s17, vcc_lo
	s_mov_b32 s1, 64
	s_branch .Lsec2_a_go

.Lsec2_a_go:
	s_nop 3
	s_add_u32 s4, s4, s17
	s_addc_u32 s5, s5, 0
	v_add_u32_e32 v144, 0x11000, v143
	v_mul_f32_e32 v160, v164, v128
	v_mul_f32_e32 v161, v164, v129
	v_mul_f32_e32 v162, v164, v130
	v_mul_f32_e32 v163, v164, v131
	v_mul_f32_e32 v188, v164, v124
	v_mul_f32_e32 v189, v164, v125
	v_mul_f32_e32 v190, v164, v126
	v_mul_f32_e32 v191, v164, v127
	v_cvt_pk_bf16_f32 v148, v160, v161
	v_cvt_pk_bf16_f32 v149, v162, v163
	v_cvt_pk_bf16_f32 v150, v188, v189
	v_cvt_pk_bf16_f32 v151, v190, v191
	ds_write_b128 v140, v[148:151]
	v_mul_f32_e32 v160, v165, v120
	v_mul_f32_e32 v161, v165, v121
	v_mul_f32_e32 v162, v165, v122
	v_mul_f32_e32 v163, v165, v123
	v_mul_f32_e32 v188, v165, v116
	v_mul_f32_e32 v189, v165, v117
	v_mul_f32_e32 v190, v165, v118
	v_mul_f32_e32 v191, v165, v119
	v_cvt_pk_bf16_f32 v148, v160, v161
	v_cvt_pk_bf16_f32 v149, v162, v163
	v_cvt_pk_bf16_f32 v150, v188, v189
	v_cvt_pk_bf16_f32 v151, v190, v191
	ds_write_b128 v140, v[148:151] offset:1024
	ds_read_b64_tr_b16 v[152:153], v141
	ds_read_b64_tr_b16 v[154:155], v141 offset:256
	ds_read_b64_tr_b16 v[156:157], v142
	ds_read_b64_tr_b16 v[158:159], v142 offset:256
	s_waitcnt lgkmcnt(0)
	global_store_dwordx4 v143, v[152:155], s[4:5]
	global_store_dwordx4 v144, v[156:159], s[4:5]
	s_add_u32 s4, s4, s1
	s_addc_u32 s5, s5, 0
	v_mul_f32_e32 v160, v166, v112
	v_mul_f32_e32 v161, v166, v113
	v_mul_f32_e32 v162, v166, v114
	v_mul_f32_e32 v163, v166, v115
	v_mul_f32_e32 v188, v166, v108
	v_mul_f32_e32 v189, v166, v109
	v_mul_f32_e32 v190, v166, v110
	v_mul_f32_e32 v191, v166, v111
	v_cvt_pk_bf16_f32 v148, v160, v161
	v_cvt_pk_bf16_f32 v149, v162, v163
	v_cvt_pk_bf16_f32 v150, v188, v189
	v_cvt_pk_bf16_f32 v151, v190, v191
	ds_write_b128 v140, v[148:151]
	v_mul_f32_e32 v160, v167, v104
	v_mul_f32_e32 v161, v167, v105
	v_mul_f32_e32 v162, v167, v106
	v_mul_f32_e32 v163, v167, v107
	v_mul_f32_e32 v188, v167, v100
	v_mul_f32_e32 v189, v167, v101
	v_mul_f32_e32 v190, v167, v102
	v_mul_f32_e32 v191, v167, v103
	v_cvt_pk_bf16_f32 v148, v160, v161
	v_cvt_pk_bf16_f32 v149, v162, v163
	v_cvt_pk_bf16_f32 v150, v188, v189
	v_cvt_pk_bf16_f32 v151, v190, v191
	ds_write_b128 v140, v[148:151] offset:1024
	ds_read_b64_tr_b16 v[152:153], v141
	ds_read_b64_tr_b16 v[154:155], v141 offset:256
	ds_read_b64_tr_b16 v[156:157], v142
	ds_read_b64_tr_b16 v[158:159], v142 offset:256
	s_waitcnt lgkmcnt(0)
	global_store_dwordx4 v143, v[152:155], s[4:5]
	global_store_dwordx4 v144, v[156:159], s[4:5]
	s_cmp_eq_u32 s48, 64
	s_cbranch_scc1 .Lsec2_a_done
	s_add_u32 s4, s4, 0xc0
	s_addc_u32 s5, s5, 0
	v_mul_f32_e32 v160, v246, v96
	v_mul_f32_e32 v161, v246, v97
	v_mul_f32_e32 v162, v246, v98
	v_mul_f32_e32 v163, v246, v99
	v_mul_f32_e32 v188, v246, v92
	v_mul_f32_e32 v189, v246, v93
	v_mul_f32_e32 v190, v246, v94
	v_mul_f32_e32 v191, v246, v95
	v_cvt_pk_bf16_f32 v148, v160, v161
	v_cvt_pk_bf16_f32 v149, v162, v163
	v_cvt_pk_bf16_f32 v150, v188, v189
	v_cvt_pk_bf16_f32 v151, v190, v191
	ds_write_b128 v140, v[148:151]
	v_mul_f32_e32 v160, v247, v88
	v_mul_f32_e32 v161, v247, v89
	v_mul_f32_e32 v162, v247, v90
	v_mul_f32_e32 v163, v247, v91
	v_mul_f32_e32 v188, v247, v84
	v_mul_f32_e32 v189, v247, v85
	v_mul_f32_e32 v190, v247, v86
	v_mul_f32_e32 v191, v247, v87
	v_cvt_pk_bf16_f32 v148, v160, v161
	v_cvt_pk_bf16_f32 v149, v162, v163
	v_cvt_pk_bf16_f32 v150, v188, v189
	v_cvt_pk_bf16_f32 v151, v190, v191
	ds_write_b128 v140, v[148:151] offset:1024
	ds_read_b64_tr_b16 v[152:153], v141
	ds_read_b64_tr_b16 v[154:155], v141 offset:256
	ds_read_b64_tr_b16 v[156:157], v142
	ds_read_b64_tr_b16 v[158:159], v142 offset:256
	s_waitcnt lgkmcnt(0)
	global_store_dwordx4 v143, v[152:155], s[4:5]
	global_store_dwordx4 v144, v[156:159], s[4:5]
	s_add_u32 s4, s4, 64
	s_addc_u32 s5, s5, 0
	v_mul_f32_e32 v160, v248, v80
	v_mul_f32_e32 v161, v248, v81
	v_mul_f32_e32 v162, v248, v82
	v_mul_f32_e32 v163, v248, v83
	v_mul_f32_e32 v188, v248, v76
	v_mul_f32_e32 v189, v248, v77
	v_mul_f32_e32 v190, v248, v78
	v_mul_f32_e32 v191, v248, v79
	v_cvt_pk_bf16_f32 v148, v160, v161
	v_cvt_pk_bf16_f32 v149, v162, v163
	v_cvt_pk_bf16_f32 v150, v188, v189
	v_cvt_pk_bf16_f32 v151, v190, v191
	ds_write_b128 v140, v[148:151]
	v_mul_f32_e32 v160, v249, v72
	v_mul_f32_e32 v161, v249, v73
	v_mul_f32_e32 v162, v249, v74
	v_mul_f32_e32 v163, v249, v75
	v_mul_f32_e32 v188, v249, v68
	v_mul_f32_e32 v189, v249, v69
	v_mul_f32_e32 v190, v249, v70
	v_mul_f32_e32 v191, v249, v71
	v_cvt_pk_bf16_f32 v148, v160, v161
	v_cvt_pk_bf16_f32 v149, v162, v163
	v_cvt_pk_bf16_f32 v150, v188, v189
	v_cvt_pk_bf16_f32 v151, v190, v191
	ds_write_b128 v140, v[148:151] offset:1024
	ds_read_b64_tr_b16 v[152:153], v141
	ds_read_b64_tr_b16 v[154:155], v141 offset:256
	ds_read_b64_tr_b16 v[156:157], v142
	ds_read_b64_tr_b16 v[158:159], v142 offset:256
	s_waitcnt lgkmcnt(0)
	global_store_dwordx4 v143, v[152:155], s[4:5]
	global_store_dwordx4 v144, v[156:159], s[4:5]

.LBB0_158:
	s_andn2_b64 vcc, exec, s[0:1]
	s_cbranch_vccnz .LBB0_166
	s_cmp_gt_i32 s2, 0
	s_mov_b64 s[0:1], -1
	s_cbranch_scc0 .LBB0_163
	s_lshl_b32 s1, s48, 8
	s_add_i32 s1, s1, s31
	s_add_i32 s3, s74, s49
	s_bfe_u32 s2, s3, 0x30006
	s_lshl_b32 s0, s2, 2
	v_mov_b32_e32 v236, s0
	global_load_dword v132, v236, s[80:81]
	global_load_dword v133, v236, s[80:81] offset:32
	s_and_b32 s42, s3, 63
	s_lshl_b32 s0, s31, 7
	s_lshl_b32 s44, s49, 6
	s_add_i32 s0, s0, s44
	s_add_i32 s0, s0, 0x20d40
	v_bfe_u32 v235, v213, 4, 2
	v_lshlrev_b32_e32 v236, 4, v235
	v_and_b32_e32 v134, 8, v181
	v_lshlrev_b32_e32 v134, 2, v134
	v_xor_b32_e32 v236, v236, v134
	v_lshl_add_u32 v168, v181, 6, v236
	v_add_u32_e32 v168, s0, v168
	v_bfe_u32 v236, v213, 2, 2
	v_lshl_add_u32 v236, v235, 3, v236
	v_lshlrev_b32_e32 v236, 6, v236
	v_and_b32_e32 v134, 1, v235
	v_lshl_add_u32 v236, v134, 5, v236
	v_and_b32_e32 v134, 3, v213
	v_lshl_add_u32 v236, v134, 3, v236
	v_add_u32_e32 v169, s0, v236
	v_xor_b32_e32 v236, 32, v236
	v_add_u32_e32 v220, s0, v236
	v_lshlrev_b32_e32 v223, 10, v181
	v_lshl_add_u32 v223, v235, 4, v223
	s_lshl_b32 s44, s42, 2
	v_lshl_add_u32 v234, v235, 5, s44
	v_lshl_add_u32 v234, v181, 8, v234
	v_add_u32_e32 v236, s42, v181
	v_mul_u32_u24_e32 v236, 0x1100, v236
	v_readlane_b32 s4, v251, 9
	v_readlane_b32 s5, v251, 10
	v_readlane_b32 s36, v251, 7
	v_readlane_b32 s37, v251, 8
	v_readlane_b32 s40, v251, 5
	v_readlane_b32 s41, v251, 6
	s_lshl_b32 s44, s3, 1
	s_add_u32 s16, s94, s44
	s_addc_u32 s17, s95, 0
	s_add_u32 s16, s16, 0x101fc00
	s_addc_u32 s17, s17, 0
	s_lshl_b32 s44, s1, 10
	s_add_u32 s16, s16, s44
	s_addc_u32 s17, s17, 0
	s_cmp_eq_u32 s48, 64
	s_cbranch_scc1 .Lsec1_a_meta
	v_lshl_add_u32 v221, v235, 4, v236
	v_add_u32_e32 v134, s31, v181
	s_lshr_b32 s44, s48, 3
	s_lshl_b32 s44, s44, 3
	s_add_i32 s44, s44, s2
	s_mul_i32 s44, s44, 0x44000
	s_and_b32 s45, s48, 7
	s_lshl_b32 s45, s45, 8
	s_add_i32 s45, s45, s31
	s_lshl_b32 s47, s45, 1
	s_add_i32 s44, s44, s47
	s_addk_i32 s44, 0x100
	s_add_i32 s45, s45, 16
	s_lshl_b32 s45, s45, 8
	s_movk_i32 s21, 0x1000
	s_mov_b32 s43, 64
	s_mov_b32 s3, 16
	s_branch .Lsec1_a_go

.Lsec1_a_go:
	s_nop 3
	s_add_u32 s36, s36, s44
	s_addc_u32 s37, s37, 0
	s_add_u32 s40, s40, s44
	s_addc_u32 s41, s41, 0
	s_add_u32 s4, s4, s45
	s_addc_u32 s5, s5, 0
	v_add_u32_e32 v222, 0x11000, v221
	global_load_dwordx4 v[188:191], v234, s[4:5]
	global_load_dwordx4 v[192:195], v234, s[4:5] offset:16
	s_waitcnt vmcnt(2)
	v_mul_f32_e32 v132, 0x3fb8aa3b, v132
	v_exp_f32_e32 v132, v132
	v_mul_f32_e32 v133, 0x3fb8aa3b, v133
	v_exp_f32_e32 v133, v133
	v_sub_u32_e32 v156, 0x7f, v134
	v_cvt_f32_u32_e32 v156, v156
	v_mul_f32_e64 v156, v156, -v132
	v_mul_f32_e32 v156, 0x3fb8aa3b, v156
	v_exp_f32_e32 v156, v156
	v_cvt_f32_u32_e32 v160, v134
	v_mul_f32_e64 v160, v160, -v133
	v_mul_f32_e32 v160, 0x3fb8aa3b, v160
	v_exp_f32_e32 v160, v160
	v_add_u32_e32 v134, s3, v134
	v_sub_u32_e32 v157, 0x7f, v134
	v_cvt_f32_u32_e32 v157, v157
	v_mul_f32_e64 v157, v157, -v132
	v_mul_f32_e32 v157, 0x3fb8aa3b, v157
	v_exp_f32_e32 v157, v157
	v_cvt_f32_u32_e32 v161, v134
	v_mul_f32_e64 v161, v161, -v133
	v_mul_f32_e32 v161, 0x3fb8aa3b, v161
	v_exp_f32_e32 v161, v161
	v_add_u32_e32 v134, s3, v134
	v_sub_u32_e32 v158, 0x7f, v134
	v_cvt_f32_u32_e32 v158, v158
	v_mul_f32_e64 v158, v158, -v132
	v_mul_f32_e32 v158, 0x3fb8aa3b, v158
	v_exp_f32_e32 v158, v158
	v_cvt_f32_u32_e32 v162, v134
	v_mul_f32_e64 v162, v162, -v133
	v_mul_f32_e32 v162, 0x3fb8aa3b, v162
	v_exp_f32_e32 v162, v162
	v_add_u32_e32 v134, s3, v134
	v_sub_u32_e32 v159, 0x7f, v134
	v_cvt_f32_u32_e32 v159, v159
	v_mul_f32_e64 v159, v159, -v132
	v_mul_f32_e32 v159, 0x3fb8aa3b, v159
	v_exp_f32_e32 v159, v159
	v_cvt_f32_u32_e32 v163, v134
	v_mul_f32_e64 v163, v163, -v133
	v_mul_f32_e32 v163, 0x3fb8aa3b, v163
	v_exp_f32_e32 v163, v163
	s_add_u32 s4, s4, s21
	s_addc_u32 s5, s5, 0
	global_load_dwordx4 v[196:199], v234, s[4:5]
	global_load_dwordx4 v[200:203], v234, s[4:5] offset:16
	s_waitcnt vmcnt(2)
	v_mul_f32_e32 v132, v164, v128
	v_mul_f32_e32 v133, v164, v129
	v_mul_f32_e32 v134, v164, v130
	v_mul_f32_e32 v135, v164, v131
	v_mul_f32_e32 v136, v164, v124
	v_mul_f32_e32 v137, v164, v125
	v_mul_f32_e32 v138, v164, v126
	v_mul_f32_e32 v139, v164, v127
	v_mul_f32_e32 v235, v189, v133
	v_mul_f32_e32 v236, v189, v132
	v_fma_f32 v132, v188, v132, -v235
	v_fma_f32 v133, v188, v133, v236
	v_mul_f32_e32 v235, v191, v135
	v_mul_f32_e32 v236, v191, v134
	v_fma_f32 v134, v190, v134, -v235
	v_fma_f32 v135, v190, v135, v236
	v_mul_f32_e32 v235, v193, v137
	v_mul_f32_e32 v236, v193, v136
	v_fma_f32 v136, v192, v136, -v235
	v_fma_f32 v137, v192, v137, v236
	v_mul_f32_e32 v235, v195, v139
	v_mul_f32_e32 v236, v195, v138
	v_fma_f32 v138, v194, v138, -v235
	v_fma_f32 v139, v194, v139, v236
	v_cvt_pk_bf16_f32 v204, v132, v133
	v_cvt_pk_bf16_f32 v205, v134, v135
	v_cvt_pk_bf16_f32 v206, v136, v137
	v_cvt_pk_bf16_f32 v207, v138, v139
	global_store_dwordx4 v223, v[204:207], s[16:17]
	s_add_u32 s16, s16, 0x4000
	s_addc_u32 s17, s17, 0
	v_mul_f32_e32 v235, v156, v132
	v_mul_f32_e32 v236, v156, v133
	v_cvt_pk_bf16_f32 v208, v235, v236
	v_mul_f32_e32 v235, v156, v134
	v_mul_f32_e32 v236, v156, v135
	v_cvt_pk_bf16_f32 v209, v235, v236
	v_mul_f32_e32 v235, v156, v136
	v_mul_f32_e32 v236, v156, v137
	v_cvt_pk_bf16_f32 v210, v235, v236
	v_mul_f32_e32 v235, v156, v138
	v_mul_f32_e32 v236, v156, v139
	v_cvt_pk_bf16_f32 v211, v235, v236
	ds_write_b128 v168, v[208:211]
	v_mul_f32_e32 v235, v160, v132
	v_mul_f32_e32 v236, v160, v133
	v_cvt_pk_bf16_f32 v140, v235, v236
	v_mul_f32_e32 v235, v160, v134
	v_mul_f32_e32 v236, v160, v135
	v_cvt_pk_bf16_f32 v141, v235, v236
	v_mul_f32_e32 v235, v160, v136
	v_mul_f32_e32 v236, v160, v137
	v_cvt_pk_bf16_f32 v142, v235, v236
	v_mul_f32_e32 v235, v160, v138
	v_mul_f32_e32 v236, v160, v139
	v_cvt_pk_bf16_f32 v143, v235, v236
	s_add_u32 s4, s4, s21
	s_addc_u32 s5, s5, 0
	global_load_dwordx4 v[188:191], v234, s[4:5]
	global_load_dwordx4 v[192:195], v234, s[4:5] offset:16
	s_waitcnt vmcnt(2)
	v_mul_f32_e32 v132, v165, v120
	v_mul_f32_e32 v133, v165, v121
	v_mul_f32_e32 v134, v165, v122
	v_mul_f32_e32 v135, v165, v123
	v_mul_f32_e32 v136, v165, v116
	v_mul_f32_e32 v137, v165, v117
	v_mul_f32_e32 v138, v165, v118
	v_mul_f32_e32 v139, v165, v119
	v_mul_f32_e32 v235, v197, v133
	v_mul_f32_e32 v236, v197, v132
	v_fma_f32 v132, v196, v132, -v235
	v_fma_f32 v133, v196, v133, v236
	v_mul_f32_e32 v235, v199, v135
	v_mul_f32_e32 v236, v199, v134
	v_fma_f32 v134, v198, v134, -v235
	v_fma_f32 v135, v198, v135, v236
	v_mul_f32_e32 v235, v201, v137
	v_mul_f32_e32 v236, v201, v136
	v_fma_f32 v136, v200, v136, -v235
	v_fma_f32 v137, v200, v137, v236
	v_mul_f32_e32 v235, v203, v139
	v_mul_f32_e32 v236, v203, v138
	v_fma_f32 v138, v202, v138, -v235
	v_fma_f32 v139, v202, v139, v236
	v_cvt_pk_bf16_f32 v204, v132, v133
	v_cvt_pk_bf16_f32 v205, v134, v135
	v_cvt_pk_bf16_f32 v206, v136, v137
	v_cvt_pk_bf16_f32 v207, v138, v139
	global_store_dwordx4 v223, v[204:207], s[16:17]
	s_add_u32 s16, s16, 0x4000
	s_addc_u32 s17, s17, 0
	v_mul_f32_e32 v235, v157, v132
	v_mul_f32_e32 v236, v157, v133
	v_cvt_pk_bf16_f32 v208, v235, v236
	v_mul_f32_e32 v235, v157, v134
	v_mul_f32_e32 v236, v157, v135
	v_cvt_pk_bf16_f32 v209, v235, v236
	v_mul_f32_e32 v235, v157, v136
	v_mul_f32_e32 v236, v157, v137
	v_cvt_pk_bf16_f32 v210, v235, v236
	v_mul_f32_e32 v235, v157, v138
	v_mul_f32_e32 v236, v157, v139
	v_cvt_pk_bf16_f32 v211, v235, v236
	ds_write_b128 v168, v[208:211] offset:1024
	v_mul_f32_e32 v235, v161, v132
	v_mul_f32_e32 v236, v161, v133
	v_cvt_pk_bf16_f32 v144, v235, v236
	v_mul_f32_e32 v235, v161, v134
	v_mul_f32_e32 v236, v161, v135
	v_cvt_pk_bf16_f32 v145, v235, v236
	v_mul_f32_e32 v235, v161, v136
	v_mul_f32_e32 v236, v161, v137
	v_cvt_pk_bf16_f32 v146, v235, v236
	v_mul_f32_e32 v235, v161, v138
	v_mul_f32_e32 v236, v161, v139
	v_cvt_pk_bf16_f32 v147, v235, v236
	ds_read_b64_tr_b16 v[204:205], v169
	ds_read_b64_tr_b16 v[206:207], v169 offset:256
	ds_read_b64_tr_b16 v[208:209], v220
	ds_read_b64_tr_b16 v[210:211], v220 offset:256
	s_waitcnt lgkmcnt(0)
	global_store_dwordx4 v221, v[204:207], s[36:37]
	global_store_dwordx4 v222, v[208:211], s[36:37]
	ds_write_b128 v168, v[140:143]
	ds_write_b128 v168, v[144:147] offset:1024
	s_nop 1
	ds_read_b64_tr_b16 v[204:205], v169
	ds_read_b64_tr_b16 v[206:207], v169 offset:256
	ds_read_b64_tr_b16 v[208:209], v220
	ds_read_b64_tr_b16 v[210:211], v220 offset:256
	s_waitcnt lgkmcnt(0)
	global_store_dwordx4 v221, v[204:207], s[40:41]
	global_store_dwordx4 v222, v[208:211], s[40:41]
	s_add_u32 s36, s36, s43
	s_addc_u32 s37, s37, 0
	s_add_u32 s40, s40, s43
	s_addc_u32 s41, s41, 0
	s_add_u32 s4, s4, s21
	s_addc_u32 s5, s5, 0
	global_load_dwordx4 v[196:199], v234, s[4:5]
	global_load_dwordx4 v[200:203], v234, s[4:5] offset:16
	s_waitcnt vmcnt(2)
	v_mul_f32_e32 v132, v166, v112
	v_mul_f32_e32 v133, v166, v113
	v_mul_f32_e32 v134, v166, v114
	v_mul_f32_e32 v135, v166, v115
	v_mul_f32_e32 v136, v166, v108
	v_mul_f32_e32 v137, v166, v109
	v_mul_f32_e32 v138, v166, v110
	v_mul_f32_e32 v139, v166, v111
	v_mul_f32_e32 v235, v189, v133
	v_mul_f32_e32 v236, v189, v132
	v_fma_f32 v132, v188, v132, -v235
	v_fma_f32 v133, v188, v133, v236
	v_mul_f32_e32 v235, v191, v135
	v_mul_f32_e32 v236, v191, v134
	v_fma_f32 v134, v190, v134, -v235
	v_fma_f32 v135, v190, v135, v236
	v_mul_f32_e32 v235, v193, v137
	v_mul_f32_e32 v236, v193, v136
	v_fma_f32 v136, v192, v136, -v235
	v_fma_f32 v137, v192, v137, v236
	v_mul_f32_e32 v235, v195, v139
	v_mul_f32_e32 v236, v195, v138
	v_fma_f32 v138, v194, v138, -v235
	v_fma_f32 v139, v194, v139, v236
	v_cvt_pk_bf16_f32 v204, v132, v133
	v_cvt_pk_bf16_f32 v205, v134, v135
	v_cvt_pk_bf16_f32 v206, v136, v137
	v_cvt_pk_bf16_f32 v207, v138, v139
	global_store_dwordx4 v223, v[204:207], s[16:17]
	s_add_u32 s16, s16, 0x4000
	s_addc_u32 s17, s17, 0
	v_mul_f32_e32 v235, v158, v132
	v_mul_f32_e32 v236, v158, v133
	v_cvt_pk_bf16_f32 v208, v235, v236
	v_mul_f32_e32 v235, v158, v134
	v_mul_f32_e32 v236, v158, v135
	v_cvt_pk_bf16_f32 v209, v235, v236
	v_mul_f32_e32 v235, v158, v136
	v_mul_f32_e32 v236, v158, v137
	v_cvt_pk_bf16_f32 v210, v235, v236
	v_mul_f32_e32 v235, v158, v138
	v_mul_f32_e32 v236, v158, v139
	v_cvt_pk_bf16_f32 v211, v235, v236
	ds_write_b128 v168, v[208:211]
	v_mul_f32_e32 v235, v162, v132
	v_mul_f32_e32 v236, v162, v133
	v_cvt_pk_bf16_f32 v140, v235, v236
	v_mul_f32_e32 v235, v162, v134
	v_mul_f32_e32 v236, v162, v135
	v_cvt_pk_bf16_f32 v141, v235, v236
	v_mul_f32_e32 v235, v162, v136
	v_mul_f32_e32 v236, v162, v137
	v_cvt_pk_bf16_f32 v142, v235, v236
	v_mul_f32_e32 v235, v162, v138
	v_mul_f32_e32 v236, v162, v139
	v_cvt_pk_bf16_f32 v143, v235, v236
	s_add_u32 s4, s4, 0x5000
	s_addc_u32 s5, s5, 0
	global_load_dwordx4 v[188:191], v234, s[4:5]
	global_load_dwordx4 v[192:195], v234, s[4:5] offset:16
	s_waitcnt vmcnt(2)
	v_mul_f32_e32 v132, v167, v104
	v_mul_f32_e32 v133, v167, v105
	v_mul_f32_e32 v134, v167, v106
	v_mul_f32_e32 v135, v167, v107
	v_mul_f32_e32 v136, v167, v100
	v_mul_f32_e32 v137, v167, v101
	v_mul_f32_e32 v138, v167, v102
	v_mul_f32_e32 v139, v167, v103
	v_mul_f32_e32 v235, v197, v133
	v_mul_f32_e32 v236, v197, v132
	v_fma_f32 v132, v196, v132, -v235
	v_fma_f32 v133, v196, v133, v236
	v_mul_f32_e32 v235, v199, v135
	v_mul_f32_e32 v236, v199, v134
	v_fma_f32 v134, v198, v134, -v235
	v_fma_f32 v135, v198, v135, v236
	v_mul_f32_e32 v235, v201, v137
	v_mul_f32_e32 v236, v201, v136
	v_fma_f32 v136, v200, v136, -v235
	v_fma_f32 v137, v200, v137, v236
	v_mul_f32_e32 v235, v203, v139
	v_mul_f32_e32 v236, v203, v138
	v_fma_f32 v138, v202, v138, -v235
	v_fma_f32 v139, v202, v139, v236
	v_cvt_pk_bf16_f32 v204, v132, v133
	v_cvt_pk_bf16_f32 v205, v134, v135
	v_cvt_pk_bf16_f32 v206, v136, v137
	v_cvt_pk_bf16_f32 v207, v138, v139
	global_store_dwordx4 v223, v[204:207], s[16:17]
	s_add_u32 s16, s16, 0x14000
	s_addc_u32 s17, s17, 0
	v_mul_f32_e32 v235, v159, v132
	v_mul_f32_e32 v236, v159, v133
	v_cvt_pk_bf16_f32 v208, v235, v236
	v_mul_f32_e32 v235, v159, v134
	v_mul_f32_e32 v236, v159, v135
	v_cvt_pk_bf16_f32 v209, v235, v236
	v_mul_f32_e32 v235, v159, v136
	v_mul_f32_e32 v236, v159, v137
	v_cvt_pk_bf16_f32 v210, v235, v236
	v_mul_f32_e32 v235, v159, v138
	v_mul_f32_e32 v236, v159, v139
	v_cvt_pk_bf16_f32 v211, v235, v236
	ds_write_b128 v168, v[208:211] offset:1024
	v_mul_f32_e32 v235, v163, v132
	v_mul_f32_e32 v236, v163, v133
	v_cvt_pk_bf16_f32 v144, v235, v236
	v_mul_f32_e32 v235, v163, v134
	v_mul_f32_e32 v236, v163, v135
	v_cvt_pk_bf16_f32 v145, v235, v236
	v_mul_f32_e32 v235, v163, v136
	v_mul_f32_e32 v236, v163, v137
	v_cvt_pk_bf16_f32 v146, v235, v236
	v_mul_f32_e32 v235, v163, v138
	v_mul_f32_e32 v236, v163, v139
	v_cvt_pk_bf16_f32 v147, v235, v236
	ds_read_b64_tr_b16 v[204:205], v169
	ds_read_b64_tr_b16 v[206:207], v169 offset:256
	ds_read_b64_tr_b16 v[208:209], v220
	ds_read_b64_tr_b16 v[210:211], v220 offset:256
	s_waitcnt lgkmcnt(0)
	global_store_dwordx4 v221, v[204:207], s[36:37]
	global_store_dwordx4 v222, v[208:211], s[36:37]
	ds_write_b128 v168, v[140:143]
	ds_write_b128 v168, v[144:147] offset:1024
	s_nop 1
	ds_read_b64_tr_b16 v[204:205], v169
	ds_read_b64_tr_b16 v[206:207], v169 offset:256
	ds_read_b64_tr_b16 v[208:209], v220
	ds_read_b64_tr_b16 v[210:211], v220 offset:256
	s_waitcnt lgkmcnt(0)
	global_store_dwordx4 v221, v[204:207], s[40:41]
	global_store_dwordx4 v222, v[208:211], s[40:41]
	s_add_u32 s36, s36, 0xc0
	s_addc_u32 s37, s37, 0
	s_add_u32 s40, s40, 0xc0
	s_addc_u32 s41, s41, 0
	s_cmp_eq_u32 s48, 64
	s_cbranch_scc1 .Lsec1_a_done
	s_add_u32 s4, s4, s21
	s_addc_u32 s5, s5, 0
	global_load_dwordx4 v[196:199], v234, s[4:5]
	global_load_dwordx4 v[200:203], v234, s[4:5] offset:16
	s_waitcnt vmcnt(2)
	v_mul_f32_e32 v132, v246, v96
	v_mul_f32_e32 v133, v246, v97
	v_mul_f32_e32 v134, v246, v98
	v_mul_f32_e32 v135, v246, v99
	v_mul_f32_e32 v136, v246, v92
	v_mul_f32_e32 v137, v246, v93
	v_mul_f32_e32 v138, v246, v94
	v_mul_f32_e32 v139, v246, v95
	v_mul_f32_e32 v235, v189, v133
	v_mul_f32_e32 v236, v189, v132
	v_fma_f32 v132, v188, v132, -v235
	v_fma_f32 v133, v188, v133, v236
	v_mul_f32_e32 v235, v191, v135
	v_mul_f32_e32 v236, v191, v134
	v_fma_f32 v134, v190, v134, -v235
	v_fma_f32 v135, v190, v135, v236
	v_mul_f32_e32 v235, v193, v137
	v_mul_f32_e32 v236, v193, v136
	v_fma_f32 v136, v192, v136, -v235
	v_fma_f32 v137, v192, v137, v236
	v_mul_f32_e32 v235, v195, v139
	v_mul_f32_e32 v236, v195, v138
	v_fma_f32 v138, v194, v138, -v235
	v_fma_f32 v139, v194, v139, v236
	v_cvt_pk_bf16_f32 v204, v132, v133
	v_cvt_pk_bf16_f32 v205, v134, v135
	v_cvt_pk_bf16_f32 v206, v136, v137
	v_cvt_pk_bf16_f32 v207, v138, v139
	global_store_dwordx4 v223, v[204:207], s[16:17]
	s_add_u32 s16, s16, 0x4000
	s_addc_u32 s17, s17, 0
	v_mul_f32_e32 v235, v156, v132
	v_mul_f32_e32 v236, v156, v133
	v_cvt_pk_bf16_f32 v208, v235, v236
	v_mul_f32_e32 v235, v156, v134
	v_mul_f32_e32 v236, v156, v135
	v_cvt_pk_bf16_f32 v209, v235, v236
	v_mul_f32_e32 v235, v156, v136
	v_mul_f32_e32 v236, v156, v137
	v_cvt_pk_bf16_f32 v210, v235, v236
	v_mul_f32_e32 v235, v156, v138
	v_mul_f32_e32 v236, v156, v139
	v_cvt_pk_bf16_f32 v211, v235, v236
	ds_write_b128 v168, v[208:211]
	v_mul_f32_e32 v235, v160, v132
	v_mul_f32_e32 v236, v160, v133
	v_cvt_pk_bf16_f32 v140, v235, v236
	v_mul_f32_e32 v235, v160, v134
	v_mul_f32_e32 v236, v160, v135
	v_cvt_pk_bf16_f32 v141, v235, v236
	v_mul_f32_e32 v235, v160, v136
	v_mul_f32_e32 v236, v160, v137
	v_cvt_pk_bf16_f32 v142, v235, v236
	v_mul_f32_e32 v235, v160, v138
	v_mul_f32_e32 v236, v160, v139
	v_cvt_pk_bf16_f32 v143, v235, v236
	s_add_u32 s4, s4, s21
	s_addc_u32 s5, s5, 0
	global_load_dwordx4 v[188:191], v234, s[4:5]
	global_load_dwordx4 v[192:195], v234, s[4:5] offset:16
	s_waitcnt vmcnt(2)
	v_mul_f32_e32 v132, v247, v88
	v_mul_f32_e32 v133, v247, v89
	v_mul_f32_e32 v134, v247, v90
	v_mul_f32_e32 v135, v247, v91
	v_mul_f32_e32 v136, v247, v84
	v_mul_f32_e32 v137, v247, v85
	v_mul_f32_e32 v138, v247, v86
	v_mul_f32_e32 v139, v247, v87
	v_mul_f32_e32 v235, v197, v133
	v_mul_f32_e32 v236, v197, v132
	v_fma_f32 v132, v196, v132, -v235
	v_fma_f32 v133, v196, v133, v236
	v_mul_f32_e32 v235, v199, v135
	v_mul_f32_e32 v236, v199, v134
	v_fma_f32 v134, v198, v134, -v235
	v_fma_f32 v135, v198, v135, v236
	v_mul_f32_e32 v235, v201, v137
	v_mul_f32_e32 v236, v201, v136
	v_fma_f32 v136, v200, v136, -v235
	v_fma_f32 v137, v200, v137, v236
	v_mul_f32_e32 v235, v203, v139
	v_mul_f32_e32 v236, v203, v138
	v_fma_f32 v138, v202, v138, -v235
	v_fma_f32 v139, v202, v139, v236
	v_cvt_pk_bf16_f32 v204, v132, v133
	v_cvt_pk_bf16_f32 v205, v134, v135
	v_cvt_pk_bf16_f32 v206, v136, v137
	v_cvt_pk_bf16_f32 v207, v138, v139
	global_store_dwordx4 v223, v[204:207], s[16:17]
	s_add_u32 s16, s16, 0x4000
	s_addc_u32 s17, s17, 0
	v_mul_f32_e32 v235, v157, v132
	v_mul_f32_e32 v236, v157, v133
	v_cvt_pk_bf16_f32 v208, v235, v236
	v_mul_f32_e32 v235, v157, v134
	v_mul_f32_e32 v236, v157, v135
	v_cvt_pk_bf16_f32 v209, v235, v236
	v_mul_f32_e32 v235, v157, v136
	v_mul_f32_e32 v236, v157, v137
	v_cvt_pk_bf16_f32 v210, v235, v236
	v_mul_f32_e32 v235, v157, v138
	v_mul_f32_e32 v236, v157, v139
	v_cvt_pk_bf16_f32 v211, v235, v236
	ds_write_b128 v168, v[208:211] offset:1024
	v_mul_f32_e32 v235, v161, v132
	v_mul_f32_e32 v236, v161, v133
	v_cvt_pk_bf16_f32 v144, v235, v236
	v_mul_f32_e32 v235, v161, v134
	v_mul_f32_e32 v236, v161, v135
	v_cvt_pk_bf16_f32 v145, v235, v236
	v_mul_f32_e32 v235, v161, v136
	v_mul_f32_e32 v236, v161, v137
	v_cvt_pk_bf16_f32 v146, v235, v236
	v_mul_f32_e32 v235, v161, v138
	v_mul_f32_e32 v236, v161, v139
	v_cvt_pk_bf16_f32 v147, v235, v236
	ds_read_b64_tr_b16 v[204:205], v169
	ds_read_b64_tr_b16 v[206:207], v169 offset:256
	ds_read_b64_tr_b16 v[208:209], v220
	ds_read_b64_tr_b16 v[210:211], v220 offset:256
	s_waitcnt lgkmcnt(0)
	global_store_dwordx4 v221, v[204:207], s[36:37]
	global_store_dwordx4 v222, v[208:211], s[36:37]
	ds_write_b128 v168, v[140:143]
	ds_write_b128 v168, v[144:147] offset:1024
	s_nop 1
	ds_read_b64_tr_b16 v[204:205], v169
	ds_read_b64_tr_b16 v[206:207], v169 offset:256
	ds_read_b64_tr_b16 v[208:209], v220
	ds_read_b64_tr_b16 v[210:211], v220 offset:256
	s_waitcnt lgkmcnt(0)
	global_store_dwordx4 v221, v[204:207], s[40:41]
	global_store_dwordx4 v222, v[208:211], s[40:41]
	s_add_u32 s36, s36, 64
	s_addc_u32 s37, s37, 0
	s_add_u32 s40, s40, 64
	s_addc_u32 s41, s41, 0
	s_add_u32 s4, s4, s21
	s_addc_u32 s5, s5, 0
	global_load_dwordx4 v[196:199], v234, s[4:5]
	global_load_dwordx4 v[200:203], v234, s[4:5] offset:16
	s_waitcnt vmcnt(2)
	v_mul_f32_e32 v132, v248, v80
	v_mul_f32_e32 v133, v248, v81
	v_mul_f32_e32 v134, v248, v82
	v_mul_f32_e32 v135, v248, v83
	v_mul_f32_e32 v136, v248, v76
	v_mul_f32_e32 v137, v248, v77
	v_mul_f32_e32 v138, v248, v78
	v_mul_f32_e32 v139, v248, v79
	v_mul_f32_e32 v235, v189, v133
	v_mul_f32_e32 v236, v189, v132
	v_fma_f32 v132, v188, v132, -v235
	v_fma_f32 v133, v188, v133, v236
	v_mul_f32_e32 v235, v191, v135
	v_mul_f32_e32 v236, v191, v134
	v_fma_f32 v134, v190, v134, -v235
	v_fma_f32 v135, v190, v135, v236
	v_mul_f32_e32 v235, v193, v137
	v_mul_f32_e32 v236, v193, v136
	v_fma_f32 v136, v192, v136, -v235
	v_fma_f32 v137, v192, v137, v236
	v_mul_f32_e32 v235, v195, v139
	v_mul_f32_e32 v236, v195, v138
	v_fma_f32 v138, v194, v138, -v235
	v_fma_f32 v139, v194, v139, v236
	v_cvt_pk_bf16_f32 v204, v132, v133
	v_cvt_pk_bf16_f32 v205, v134, v135
	v_cvt_pk_bf16_f32 v206, v136, v137
	v_cvt_pk_bf16_f32 v207, v138, v139
	global_store_dwordx4 v223, v[204:207], s[16:17]
	s_add_u32 s16, s16, 0x4000
	s_addc_u32 s17, s17, 0
	v_mul_f32_e32 v235, v158, v132
	v_mul_f32_e32 v236, v158, v133
	v_cvt_pk_bf16_f32 v208, v235, v236
	v_mul_f32_e32 v235, v158, v134
	v_mul_f32_e32 v236, v158, v135
	v_cvt_pk_bf16_f32 v209, v235, v236
	v_mul_f32_e32 v235, v158, v136
	v_mul_f32_e32 v236, v158, v137
	v_cvt_pk_bf16_f32 v210, v235, v236
	v_mul_f32_e32 v235, v158, v138
	v_mul_f32_e32 v236, v158, v139
	v_cvt_pk_bf16_f32 v211, v235, v236
	ds_write_b128 v168, v[208:211]
	v_mul_f32_e32 v235, v162, v132
	v_mul_f32_e32 v236, v162, v133
	v_cvt_pk_bf16_f32 v140, v235, v236
	v_mul_f32_e32 v235, v162, v134
	v_mul_f32_e32 v236, v162, v135
	v_cvt_pk_bf16_f32 v141, v235, v236
	v_mul_f32_e32 v235, v162, v136
	v_mul_f32_e32 v236, v162, v137
	v_cvt_pk_bf16_f32 v142, v235, v236
	v_mul_f32_e32 v235, v162, v138
	v_mul_f32_e32 v236, v162, v139
	v_cvt_pk_bf16_f32 v143, v235, v236
	s_waitcnt vmcnt(0)
	v_mul_f32_e32 v132, v249, v72
	v_mul_f32_e32 v133, v249, v73
	v_mul_f32_e32 v134, v249, v74
	v_mul_f32_e32 v135, v249, v75
	v_mul_f32_e32 v136, v249, v68
	v_mul_f32_e32 v137, v249, v69
	v_mul_f32_e32 v138, v249, v70
	v_mul_f32_e32 v139, v249, v71
	v_mul_f32_e32 v235, v197, v133
	v_mul_f32_e32 v236, v197, v132
	v_fma_f32 v132, v196, v132, -v235
	v_fma_f32 v133, v196, v133, v236
	v_mul_f32_e32 v235, v199, v135
	v_mul_f32_e32 v236, v199, v134
	v_fma_f32 v134, v198, v134, -v235
	v_fma_f32 v135, v198, v135, v236
	v_mul_f32_e32 v235, v201, v137
	v_mul_f32_e32 v236, v201, v136
	v_fma_f32 v136, v200, v136, -v235
	v_fma_f32 v137, v200, v137, v236
	v_mul_f32_e32 v235, v203, v139
	v_mul_f32_e32 v236, v203, v138
	v_fma_f32 v138, v202, v138, -v235
	v_fma_f32 v139, v202, v139, v236
	v_cvt_pk_bf16_f32 v204, v132, v133
	v_cvt_pk_bf16_f32 v205, v134, v135
	v_cvt_pk_bf16_f32 v206, v136, v137
	v_cvt_pk_bf16_f32 v207, v138, v139
	global_store_dwordx4 v223, v[204:207], s[16:17]
	s_add_u32 s16, s16, 0x14000
	s_addc_u32 s17, s17, 0
	v_mul_f32_e32 v235, v159, v132
	v_mul_f32_e32 v236, v159, v133
	v_cvt_pk_bf16_f32 v208, v235, v236
	v_mul_f32_e32 v235, v159, v134
	v_mul_f32_e32 v236, v159, v135
	v_cvt_pk_bf16_f32 v209, v235, v236
	v_mul_f32_e32 v235, v159, v136
	v_mul_f32_e32 v236, v159, v137
	v_cvt_pk_bf16_f32 v210, v235, v236
	v_mul_f32_e32 v235, v159, v138
	v_mul_f32_e32 v236, v159, v139
	v_cvt_pk_bf16_f32 v211, v235, v236
	ds_write_b128 v168, v[208:211] offset:1024
	v_mul_f32_e32 v235, v163, v132
	v_mul_f32_e32 v236, v163, v133
	v_cvt_pk_bf16_f32 v144, v235, v236
	v_mul_f32_e32 v235, v163, v134
	v_mul_f32_e32 v236, v163, v135
	v_cvt_pk_bf16_f32 v145, v235, v236
	v_mul_f32_e32 v235, v163, v136
	v_mul_f32_e32 v236, v163, v137
	v_cvt_pk_bf16_f32 v146, v235, v236
	v_mul_f32_e32 v235, v163, v138
	v_mul_f32_e32 v236, v163, v139
	v_cvt_pk_bf16_f32 v147, v235, v236
	ds_read_b64_tr_b16 v[204:205], v169
	ds_read_b64_tr_b16 v[206:207], v169 offset:256
	ds_read_b64_tr_b16 v[208:209], v220
	ds_read_b64_tr_b16 v[210:211], v220 offset:256
	s_waitcnt lgkmcnt(0)
	global_store_dwordx4 v221, v[204:207], s[36:37]
	global_store_dwordx4 v222, v[208:211], s[36:37]
	ds_write_b128 v168, v[140:143]
	ds_write_b128 v168, v[144:147] offset:1024
	s_nop 1
	ds_read_b64_tr_b16 v[204:205], v169
	ds_read_b64_tr_b16 v[206:207], v169 offset:256
	ds_read_b64_tr_b16 v[208:209], v220
	ds_read_b64_tr_b16 v[210:211], v220 offset:256
	s_waitcnt lgkmcnt(0)
	global_store_dwordx4 v221, v[204:207], s[40:41]
	global_store_dwordx4 v222, v[208:211], s[40:41]

.LBB0_229:
	s_andn2_b64 vcc, exec, s[0:1]
	s_cbranch_vccnz .LBB0_45
	s_cmp_lt_i32 s17, 1
	s_mov_b64 s[0:1], -1
	s_cbranch_scc1 .LBB0_239
	s_cmp_gt_i32 s17, 1
	s_cbranch_scc0 .LBB0_235
	s_lshl_b32 s0, s31, 7
	s_lshl_b32 s3, s49, 6
	s_add_i32 s0, s0, s3
	s_add_i32 s0, s0, 0x20d40
	v_bfe_u32 v81, v213, 4, 2
	v_lshlrev_b32_e32 v82, 4, v81
	v_and_b32_e32 v83, 8, v181
	v_lshlrev_b32_e32 v83, 2, v83
	v_xor_b32_e32 v82, v82, v83
	v_lshl_add_u32 v76, v181, 6, v82
	v_add_u32_e32 v76, s0, v76
	v_bfe_u32 v82, v213, 2, 2
	v_lshl_add_u32 v82, v81, 3, v82
	v_lshlrev_b32_e32 v82, 6, v82
	v_and_b32_e32 v83, 1, v81
	v_lshl_add_u32 v82, v83, 5, v82
	v_and_b32_e32 v83, 3, v213
	v_lshl_add_u32 v82, v83, 3, v82
	v_add_u32_e32 v77, s0, v82
	v_xor_b32_e32 v82, 32, v82
	v_add_u32_e32 v78, s0, v82
	v_add_u32_e32 v84, s49, v181
	v_mul_u32_u24_e32 v84, 0x1100, v84
	v_readlane_b32 s4, v255, 20
	v_readlane_b32 s5, v255, 21
	s_lshr_b32 s3, s74, 7
	s_add_i32 s3, s3, -7
	s_cmp_eq_u32 s48, 64
	s_cbranch_scc1 .Lsec2_b_meta
	v_lshl_add_u32 v79, v81, 4, v84
	s_lshr_b32 s17, s48, 3
	s_lshl_b32 s17, s17, 3
	s_add_i32 s17, s17, s3
	s_mul_i32 s17, s17, 0x88000
	s_and_b32 vcc_lo, s48, 7
	s_lshl_b32 vcc_lo, vcc_lo, 9
	s_lshl_b32 vcc_hi, s31, 1
	s_add_i32 vcc_lo, vcc_lo, vcc_hi
	s_addk_i32 vcc_lo, 0x100
	s_add_i32 s17, s17, vcc_lo
	s_mov_b32 s1, 64
	s_branch .Lsec2_b_go

.Lsec2_b_go:
	s_nop 3
	s_add_u32 s4, s4, s17
	s_addc_u32 s5, s5, 0
	v_add_u32_e32 v80, 0x11000, v79
	v_mul_f32_e32 v100, v164, v64
	v_mul_f32_e32 v101, v164, v65
	v_mul_f32_e32 v102, v164, v66
	v_mul_f32_e32 v103, v164, v67
	v_mul_f32_e32 v104, v164, v60
	v_mul_f32_e32 v105, v164, v61
	v_mul_f32_e32 v106, v164, v62
	v_mul_f32_e32 v107, v164, v63
	v_cvt_pk_bf16_f32 v88, v100, v101
	v_cvt_pk_bf16_f32 v89, v102, v103
	v_cvt_pk_bf16_f32 v90, v104, v105
	v_cvt_pk_bf16_f32 v91, v106, v107
	ds_write_b128 v76, v[88:91]
	v_mul_f32_e32 v100, v165, v56
	v_mul_f32_e32 v101, v165, v57
	v_mul_f32_e32 v102, v165, v58
	v_mul_f32_e32 v103, v165, v59
	v_mul_f32_e32 v104, v165, v52
	v_mul_f32_e32 v105, v165, v53
	v_mul_f32_e32 v106, v165, v54
	v_mul_f32_e32 v107, v165, v55
	v_cvt_pk_bf16_f32 v88, v100, v101
	v_cvt_pk_bf16_f32 v89, v102, v103
	v_cvt_pk_bf16_f32 v90, v104, v105
	v_cvt_pk_bf16_f32 v91, v106, v107
	ds_write_b128 v76, v[88:91] offset:1024
	ds_read_b64_tr_b16 v[92:93], v77
	ds_read_b64_tr_b16 v[94:95], v77 offset:256
	ds_read_b64_tr_b16 v[96:97], v78
	ds_read_b64_tr_b16 v[98:99], v78 offset:256
	s_waitcnt lgkmcnt(0)
	global_store_dwordx4 v79, v[92:95], s[4:5]
	global_store_dwordx4 v80, v[96:99], s[4:5]
	s_add_u32 s4, s4, s1
	s_addc_u32 s5, s5, 0
	v_mul_f32_e32 v100, v166, v48
	v_mul_f32_e32 v101, v166, v49
	v_mul_f32_e32 v102, v166, v50
	v_mul_f32_e32 v103, v166, v51
	v_mul_f32_e32 v104, v166, v44
	v_mul_f32_e32 v105, v166, v45
	v_mul_f32_e32 v106, v166, v46
	v_mul_f32_e32 v107, v166, v47
	v_cvt_pk_bf16_f32 v88, v100, v101
	v_cvt_pk_bf16_f32 v89, v102, v103
	v_cvt_pk_bf16_f32 v90, v104, v105
	v_cvt_pk_bf16_f32 v91, v106, v107
	ds_write_b128 v76, v[88:91]
	v_mul_f32_e32 v100, v167, v40
	v_mul_f32_e32 v101, v167, v41
	v_mul_f32_e32 v102, v167, v42
	v_mul_f32_e32 v103, v167, v43
	v_mul_f32_e32 v104, v167, v36
	v_mul_f32_e32 v105, v167, v37
	v_mul_f32_e32 v106, v167, v38
	v_mul_f32_e32 v107, v167, v39
	v_cvt_pk_bf16_f32 v88, v100, v101
	v_cvt_pk_bf16_f32 v89, v102, v103
	v_cvt_pk_bf16_f32 v90, v104, v105
	v_cvt_pk_bf16_f32 v91, v106, v107
	ds_write_b128 v76, v[88:91] offset:1024
	ds_read_b64_tr_b16 v[92:93], v77
	ds_read_b64_tr_b16 v[94:95], v77 offset:256
	ds_read_b64_tr_b16 v[96:97], v78
	ds_read_b64_tr_b16 v[98:99], v78 offset:256
	s_waitcnt lgkmcnt(0)
	global_store_dwordx4 v79, v[92:95], s[4:5]
	global_store_dwordx4 v80, v[96:99], s[4:5]
	s_cmp_eq_u32 s48, 64
	s_cbranch_scc1 .Lsec2_b_done
	s_add_u32 s4, s4, 0xc0
	s_addc_u32 s5, s5, 0
	v_mul_f32_e32 v100, v246, v32
	v_mul_f32_e32 v101, v246, v33
	v_mul_f32_e32 v102, v246, v34
	v_mul_f32_e32 v103, v246, v35
	v_mul_f32_e32 v104, v246, v28
	v_mul_f32_e32 v105, v246, v29
	v_mul_f32_e32 v106, v246, v30
	v_mul_f32_e32 v107, v246, v31
	v_cvt_pk_bf16_f32 v88, v100, v101
	v_cvt_pk_bf16_f32 v89, v102, v103
	v_cvt_pk_bf16_f32 v90, v104, v105
	v_cvt_pk_bf16_f32 v91, v106, v107
	ds_write_b128 v76, v[88:91]
	v_mul_f32_e32 v100, v247, v24
	v_mul_f32_e32 v101, v247, v25
	v_mul_f32_e32 v102, v247, v26
	v_mul_f32_e32 v103, v247, v27
	v_mul_f32_e32 v104, v247, v20
	v_mul_f32_e32 v105, v247, v21
	v_mul_f32_e32 v106, v247, v22
	v_mul_f32_e32 v107, v247, v23
	v_cvt_pk_bf16_f32 v88, v100, v101
	v_cvt_pk_bf16_f32 v89, v102, v103
	v_cvt_pk_bf16_f32 v90, v104, v105
	v_cvt_pk_bf16_f32 v91, v106, v107
	ds_write_b128 v76, v[88:91] offset:1024
	ds_read_b64_tr_b16 v[92:93], v77
	ds_read_b64_tr_b16 v[94:95], v77 offset:256
	ds_read_b64_tr_b16 v[96:97], v78
	ds_read_b64_tr_b16 v[98:99], v78 offset:256
	s_waitcnt lgkmcnt(0)
	global_store_dwordx4 v79, v[92:95], s[4:5]
	global_store_dwordx4 v80, v[96:99], s[4:5]
	s_add_u32 s4, s4, 64
	s_addc_u32 s5, s5, 0
	v_mul_f32_e32 v100, v248, v16
	v_mul_f32_e32 v101, v248, v17
	v_mul_f32_e32 v102, v248, v18
	v_mul_f32_e32 v103, v248, v19
	v_mul_f32_e32 v104, v248, v12
	v_mul_f32_e32 v105, v248, v13
	v_mul_f32_e32 v106, v248, v14
	v_mul_f32_e32 v107, v248, v15
	v_cvt_pk_bf16_f32 v88, v100, v101
	v_cvt_pk_bf16_f32 v89, v102, v103
	v_cvt_pk_bf16_f32 v90, v104, v105
	v_cvt_pk_bf16_f32 v91, v106, v107
	ds_write_b128 v76, v[88:91]
	v_mul_f32_e32 v100, v249, v8
	v_mul_f32_e32 v101, v249, v9
	v_mul_f32_e32 v102, v249, v10
	v_mul_f32_e32 v103, v249, v11
	v_mul_f32_e32 v104, v249, v4
	v_mul_f32_e32 v105, v249, v5
	v_mul_f32_e32 v106, v249, v6
	v_mul_f32_e32 v107, v249, v7
	v_cvt_pk_bf16_f32 v88, v100, v101
	v_cvt_pk_bf16_f32 v89, v102, v103
	v_cvt_pk_bf16_f32 v90, v104, v105
	v_cvt_pk_bf16_f32 v91, v106, v107
	ds_write_b128 v76, v[88:91] offset:1024
	ds_read_b64_tr_b16 v[92:93], v77
	ds_read_b64_tr_b16 v[94:95], v77 offset:256
	ds_read_b64_tr_b16 v[96:97], v78
	ds_read_b64_tr_b16 v[98:99], v78 offset:256
	s_waitcnt lgkmcnt(0)
	global_store_dwordx4 v79, v[92:95], s[4:5]
	global_store_dwordx4 v80, v[96:99], s[4:5]

.LBB0_235:
	s_andn2_b64 vcc, exec, s[0:1]
	s_cbranch_vccnz .LBB0_238
	s_lshl_b32 s1, s48, 8
	s_add_i32 s1, s1, s31
	s_add_i32 s3, s74, s49
	s_addk_i32 s3, 0x80
	s_bfe_u32 s2, s3, 0x30006
	s_lshl_b32 s0, s2, 2
	v_mov_b32_e32 v116, s0
	global_load_dword v108, v116, s[80:81]
	global_load_dword v109, v116, s[80:81] offset:32
	s_and_b32 s42, s3, 63
	s_lshl_b32 s0, s31, 7
	s_lshl_b32 s44, s49, 6
	s_add_i32 s0, s0, s44
	s_add_i32 s0, s0, 0x20d40
	v_bfe_u32 v91, v213, 4, 2
	v_lshlrev_b32_e32 v116, 4, v91
	v_and_b32_e32 v110, 8, v181
	v_lshlrev_b32_e32 v110, 2, v110
	v_xor_b32_e32 v116, v116, v110
	v_lshl_add_u32 v84, v181, 6, v116
	v_add_u32_e32 v84, s0, v84
	v_bfe_u32 v116, v213, 2, 2
	v_lshl_add_u32 v116, v91, 3, v116
	v_lshlrev_b32_e32 v116, 6, v116
	v_and_b32_e32 v110, 1, v91
	v_lshl_add_u32 v116, v110, 5, v116
	v_and_b32_e32 v110, 3, v213
	v_lshl_add_u32 v116, v110, 3, v116
	v_add_u32_e32 v85, s0, v116
	v_xor_b32_e32 v116, 32, v116
	v_add_u32_e32 v86, s0, v116
	v_lshlrev_b32_e32 v89, 10, v181
	v_lshl_add_u32 v89, v91, 4, v89
	s_lshl_b32 s44, s42, 2
	v_lshl_add_u32 v90, v91, 5, s44
	v_lshl_add_u32 v90, v181, 8, v90
	v_add_u32_e32 v116, s42, v181
	v_mul_u32_u24_e32 v116, 0x1100, v116
	v_readlane_b32 s4, v251, 9
	v_readlane_b32 s5, v251, 10
	v_readlane_b32 s36, v251, 7
	v_readlane_b32 s37, v251, 8
	v_readlane_b32 s40, v251, 5
	v_readlane_b32 s41, v251, 6
	s_lshl_b32 s44, s3, 1
	s_add_u32 s16, s94, s44
	s_addc_u32 s17, s95, 0
	s_add_u32 s16, s16, 0x101fc00
	s_addc_u32 s17, s17, 0
	s_lshl_b32 s44, s1, 10
	s_add_u32 s16, s16, s44
	s_addc_u32 s17, s17, 0
	s_cmp_eq_u32 s48, 64
	s_cbranch_scc1 .Lsec1_b_meta
	v_lshl_add_u32 v87, v91, 4, v116
	v_add_u32_e32 v110, s31, v181
	s_lshr_b32 s44, s48, 3
	s_lshl_b32 s44, s44, 3
	s_add_i32 s44, s44, s2
	s_mul_i32 s44, s44, 0x44000
	s_and_b32 s45, s48, 7
	s_lshl_b32 s45, s45, 8
	s_add_i32 s45, s45, s31
	s_lshl_b32 s47, s45, 1
	s_add_i32 s44, s44, s47
	s_addk_i32 s44, 0x100
	s_add_i32 s45, s45, 16
	s_lshl_b32 s45, s45, 8
	s_movk_i32 s21, 0x1000
	s_mov_b32 s43, 64
	s_mov_b32 s3, 16
	s_branch .Lsec1_b_go

.Lsec1_b_go:
	s_nop 3
	s_add_u32 s36, s36, s44
	s_addc_u32 s37, s37, 0
	s_add_u32 s40, s40, s44
	s_addc_u32 s41, s41, 0
	s_add_u32 s4, s4, s45
	s_addc_u32 s5, s5, 0
	v_add_u32_e32 v88, 0x11000, v87
	global_load_dwordx4 v[92:95], v90, s[4:5]
	global_load_dwordx4 v[96:99], v90, s[4:5] offset:16
	s_waitcnt vmcnt(2)
	v_mul_f32_e32 v108, 0x3fb8aa3b, v108
	v_exp_f32_e32 v108, v108
	v_mul_f32_e32 v109, 0x3fb8aa3b, v109
	v_exp_f32_e32 v109, v109
	v_sub_u32_e32 v76, 0x7f, v110
	v_cvt_f32_u32_e32 v76, v76
	v_mul_f32_e64 v76, v76, -v108
	v_mul_f32_e32 v76, 0x3fb8aa3b, v76
	v_exp_f32_e32 v76, v76
	v_cvt_f32_u32_e32 v80, v110
	v_mul_f32_e64 v80, v80, -v109
	v_mul_f32_e32 v80, 0x3fb8aa3b, v80
	v_exp_f32_e32 v80, v80
	v_add_u32_e32 v110, s3, v110
	v_sub_u32_e32 v77, 0x7f, v110
	v_cvt_f32_u32_e32 v77, v77
	v_mul_f32_e64 v77, v77, -v108
	v_mul_f32_e32 v77, 0x3fb8aa3b, v77
	v_exp_f32_e32 v77, v77
	v_cvt_f32_u32_e32 v81, v110
	v_mul_f32_e64 v81, v81, -v109
	v_mul_f32_e32 v81, 0x3fb8aa3b, v81
	v_exp_f32_e32 v81, v81
	v_add_u32_e32 v110, s3, v110
	v_sub_u32_e32 v78, 0x7f, v110
	v_cvt_f32_u32_e32 v78, v78
	v_mul_f32_e64 v78, v78, -v108
	v_mul_f32_e32 v78, 0x3fb8aa3b, v78
	v_exp_f32_e32 v78, v78
	v_cvt_f32_u32_e32 v82, v110
	v_mul_f32_e64 v82, v82, -v109
	v_mul_f32_e32 v82, 0x3fb8aa3b, v82
	v_exp_f32_e32 v82, v82
	v_add_u32_e32 v110, s3, v110
	v_sub_u32_e32 v79, 0x7f, v110
	v_cvt_f32_u32_e32 v79, v79
	v_mul_f32_e64 v79, v79, -v108
	v_mul_f32_e32 v79, 0x3fb8aa3b, v79
	v_exp_f32_e32 v79, v79
	v_cvt_f32_u32_e32 v83, v110
	v_mul_f32_e64 v83, v83, -v109
	v_mul_f32_e32 v83, 0x3fb8aa3b, v83
	v_exp_f32_e32 v83, v83
	s_add_u32 s4, s4, s21
	s_addc_u32 s5, s5, 0
	global_load_dwordx4 v[100:103], v90, s[4:5]
	global_load_dwordx4 v[104:107], v90, s[4:5] offset:16
	s_waitcnt vmcnt(2)
	v_mul_f32_e32 v108, v164, v64
	v_mul_f32_e32 v109, v164, v65
	v_mul_f32_e32 v110, v164, v66
	v_mul_f32_e32 v111, v164, v67
	v_mul_f32_e32 v112, v164, v60
	v_mul_f32_e32 v113, v164, v61
	v_mul_f32_e32 v114, v164, v62
	v_mul_f32_e32 v115, v164, v63
	v_mul_f32_e32 v91, v93, v109
	v_mul_f32_e32 v116, v93, v108
	v_fma_f32 v108, v92, v108, -v91
	v_fma_f32 v109, v92, v109, v116
	v_mul_f32_e32 v91, v95, v111
	v_mul_f32_e32 v116, v95, v110
	v_fma_f32 v110, v94, v110, -v91
	v_fma_f32 v111, v94, v111, v116
	v_mul_f32_e32 v91, v97, v113
	v_mul_f32_e32 v116, v97, v112
	v_fma_f32 v112, v96, v112, -v91
	v_fma_f32 v113, v96, v113, v116
	v_mul_f32_e32 v91, v99, v115
	v_mul_f32_e32 v116, v99, v114
	v_fma_f32 v114, v98, v114, -v91
	v_fma_f32 v115, v98, v115, v116
	v_cvt_pk_bf16_f32 v120, v108, v109
	v_cvt_pk_bf16_f32 v121, v110, v111
	v_cvt_pk_bf16_f32 v122, v112, v113
	v_cvt_pk_bf16_f32 v123, v114, v115
	global_store_dwordx4 v89, v[120:123], s[16:17]
	s_add_u32 s16, s16, 0x4000
	s_addc_u32 s17, s17, 0
	v_mul_f32_e32 v91, v76, v108
	v_mul_f32_e32 v116, v76, v109
	v_cvt_pk_bf16_f32 v124, v91, v116
	v_mul_f32_e32 v91, v76, v110
	v_mul_f32_e32 v116, v76, v111
	v_cvt_pk_bf16_f32 v125, v91, v116
	v_mul_f32_e32 v91, v76, v112
	v_mul_f32_e32 v116, v76, v113
	v_cvt_pk_bf16_f32 v126, v91, v116
	v_mul_f32_e32 v91, v76, v114
	v_mul_f32_e32 v116, v76, v115
	v_cvt_pk_bf16_f32 v127, v91, v116
	ds_write_b128 v84, v[124:127]
	v_mul_f32_e32 v91, v80, v108
	v_mul_f32_e32 v116, v80, v109
	v_cvt_pk_bf16_f32 v128, v91, v116
	v_mul_f32_e32 v91, v80, v110
	v_mul_f32_e32 v116, v80, v111
	v_cvt_pk_bf16_f32 v129, v91, v116
	v_mul_f32_e32 v91, v80, v112
	v_mul_f32_e32 v116, v80, v113
	v_cvt_pk_bf16_f32 v130, v91, v116
	v_mul_f32_e32 v91, v80, v114
	v_mul_f32_e32 v116, v80, v115
	v_cvt_pk_bf16_f32 v131, v91, v116
	s_add_u32 s4, s4, s21
	s_addc_u32 s5, s5, 0
	global_load_dwordx4 v[92:95], v90, s[4:5]
	global_load_dwordx4 v[96:99], v90, s[4:5] offset:16
	s_waitcnt vmcnt(2)
	v_mul_f32_e32 v108, v165, v56
	v_mul_f32_e32 v109, v165, v57
	v_mul_f32_e32 v110, v165, v58
	v_mul_f32_e32 v111, v165, v59
	v_mul_f32_e32 v112, v165, v52
	v_mul_f32_e32 v113, v165, v53
	v_mul_f32_e32 v114, v165, v54
	v_mul_f32_e32 v115, v165, v55
	v_mul_f32_e32 v91, v101, v109
	v_mul_f32_e32 v116, v101, v108
	v_fma_f32 v108, v100, v108, -v91
	v_fma_f32 v109, v100, v109, v116
	v_mul_f32_e32 v91, v103, v111
	v_mul_f32_e32 v116, v103, v110
	v_fma_f32 v110, v102, v110, -v91
	v_fma_f32 v111, v102, v111, v116
	v_mul_f32_e32 v91, v105, v113
	v_mul_f32_e32 v116, v105, v112
	v_fma_f32 v112, v104, v112, -v91
	v_fma_f32 v113, v104, v113, v116
	v_mul_f32_e32 v91, v107, v115
	v_mul_f32_e32 v116, v107, v114
	v_fma_f32 v114, v106, v114, -v91
	v_fma_f32 v115, v106, v115, v116
	v_cvt_pk_bf16_f32 v120, v108, v109
	v_cvt_pk_bf16_f32 v121, v110, v111
	v_cvt_pk_bf16_f32 v122, v112, v113
	v_cvt_pk_bf16_f32 v123, v114, v115
	global_store_dwordx4 v89, v[120:123], s[16:17]
	s_add_u32 s16, s16, 0x4000
	s_addc_u32 s17, s17, 0
	v_mul_f32_e32 v91, v77, v108
	v_mul_f32_e32 v116, v77, v109
	v_cvt_pk_bf16_f32 v124, v91, v116
	v_mul_f32_e32 v91, v77, v110
	v_mul_f32_e32 v116, v77, v111
	v_cvt_pk_bf16_f32 v125, v91, v116
	v_mul_f32_e32 v91, v77, v112
	v_mul_f32_e32 v116, v77, v113
	v_cvt_pk_bf16_f32 v126, v91, v116
	v_mul_f32_e32 v91, v77, v114
	v_mul_f32_e32 v116, v77, v115
	v_cvt_pk_bf16_f32 v127, v91, v116
	ds_write_b128 v84, v[124:127] offset:1024
	v_mul_f32_e32 v91, v81, v108
	v_mul_f32_e32 v116, v81, v109
	v_cvt_pk_bf16_f32 v132, v91, v116
	v_mul_f32_e32 v91, v81, v110
	v_mul_f32_e32 v116, v81, v111
	v_cvt_pk_bf16_f32 v133, v91, v116
	v_mul_f32_e32 v91, v81, v112
	v_mul_f32_e32 v116, v81, v113
	v_cvt_pk_bf16_f32 v134, v91, v116
	v_mul_f32_e32 v91, v81, v114
	v_mul_f32_e32 v116, v81, v115
	v_cvt_pk_bf16_f32 v135, v91, v116
	ds_read_b64_tr_b16 v[120:121], v85
	ds_read_b64_tr_b16 v[122:123], v85 offset:256
	ds_read_b64_tr_b16 v[124:125], v86
	ds_read_b64_tr_b16 v[126:127], v86 offset:256
	s_waitcnt lgkmcnt(0)
	global_store_dwordx4 v87, v[120:123], s[36:37]
	global_store_dwordx4 v88, v[124:127], s[36:37]
	ds_write_b128 v84, v[128:131]
	ds_write_b128 v84, v[132:135] offset:1024
	s_nop 1
	ds_read_b64_tr_b16 v[120:121], v85
	ds_read_b64_tr_b16 v[122:123], v85 offset:256
	ds_read_b64_tr_b16 v[124:125], v86
	ds_read_b64_tr_b16 v[126:127], v86 offset:256
	s_waitcnt lgkmcnt(0)
	global_store_dwordx4 v87, v[120:123], s[40:41]
	global_store_dwordx4 v88, v[124:127], s[40:41]
	s_add_u32 s36, s36, s43
	s_addc_u32 s37, s37, 0
	s_add_u32 s40, s40, s43
	s_addc_u32 s41, s41, 0
	s_add_u32 s4, s4, s21
	s_addc_u32 s5, s5, 0
	global_load_dwordx4 v[100:103], v90, s[4:5]
	global_load_dwordx4 v[104:107], v90, s[4:5] offset:16
	s_waitcnt vmcnt(2)
	v_mul_f32_e32 v108, v166, v48
	v_mul_f32_e32 v109, v166, v49
	v_mul_f32_e32 v110, v166, v50
	v_mul_f32_e32 v111, v166, v51
	v_mul_f32_e32 v112, v166, v44
	v_mul_f32_e32 v113, v166, v45
	v_mul_f32_e32 v114, v166, v46
	v_mul_f32_e32 v115, v166, v47
	v_mul_f32_e32 v91, v93, v109
	v_mul_f32_e32 v116, v93, v108
	v_fma_f32 v108, v92, v108, -v91
	v_fma_f32 v109, v92, v109, v116
	v_mul_f32_e32 v91, v95, v111
	v_mul_f32_e32 v116, v95, v110
	v_fma_f32 v110, v94, v110, -v91
	v_fma_f32 v111, v94, v111, v116
	v_mul_f32_e32 v91, v97, v113
	v_mul_f32_e32 v116, v97, v112
	v_fma_f32 v112, v96, v112, -v91
	v_fma_f32 v113, v96, v113, v116
	v_mul_f32_e32 v91, v99, v115
	v_mul_f32_e32 v116, v99, v114
	v_fma_f32 v114, v98, v114, -v91
	v_fma_f32 v115, v98, v115, v116
	v_cvt_pk_bf16_f32 v120, v108, v109
	v_cvt_pk_bf16_f32 v121, v110, v111
	v_cvt_pk_bf16_f32 v122, v112, v113
	v_cvt_pk_bf16_f32 v123, v114, v115
	global_store_dwordx4 v89, v[120:123], s[16:17]
	s_add_u32 s16, s16, 0x4000
	s_addc_u32 s17, s17, 0
	v_mul_f32_e32 v91, v78, v108
	v_mul_f32_e32 v116, v78, v109
	v_cvt_pk_bf16_f32 v124, v91, v116
	v_mul_f32_e32 v91, v78, v110
	v_mul_f32_e32 v116, v78, v111
	v_cvt_pk_bf16_f32 v125, v91, v116
	v_mul_f32_e32 v91, v78, v112
	v_mul_f32_e32 v116, v78, v113
	v_cvt_pk_bf16_f32 v126, v91, v116
	v_mul_f32_e32 v91, v78, v114
	v_mul_f32_e32 v116, v78, v115
	v_cvt_pk_bf16_f32 v127, v91, v116
	ds_write_b128 v84, v[124:127]
	v_mul_f32_e32 v91, v82, v108
	v_mul_f32_e32 v116, v82, v109
	v_cvt_pk_bf16_f32 v128, v91, v116
	v_mul_f32_e32 v91, v82, v110
	v_mul_f32_e32 v116, v82, v111
	v_cvt_pk_bf16_f32 v129, v91, v116
	v_mul_f32_e32 v91, v82, v112
	v_mul_f32_e32 v116, v82, v113
	v_cvt_pk_bf16_f32 v130, v91, v116
	v_mul_f32_e32 v91, v82, v114
	v_mul_f32_e32 v116, v82, v115
	v_cvt_pk_bf16_f32 v131, v91, v116
	s_add_u32 s4, s4, 0x5000
	s_addc_u32 s5, s5, 0
	global_load_dwordx4 v[92:95], v90, s[4:5]
	global_load_dwordx4 v[96:99], v90, s[4:5] offset:16
	s_waitcnt vmcnt(2)
	v_mul_f32_e32 v108, v167, v40
	v_mul_f32_e32 v109, v167, v41
	v_mul_f32_e32 v110, v167, v42
	v_mul_f32_e32 v111, v167, v43
	v_mul_f32_e32 v112, v167, v36
	v_mul_f32_e32 v113, v167, v37
	v_mul_f32_e32 v114, v167, v38
	v_mul_f32_e32 v115, v167, v39
	v_mul_f32_e32 v91, v101, v109
	v_mul_f32_e32 v116, v101, v108
	v_fma_f32 v108, v100, v108, -v91
	v_fma_f32 v109, v100, v109, v116
	v_mul_f32_e32 v91, v103, v111
	v_mul_f32_e32 v116, v103, v110
	v_fma_f32 v110, v102, v110, -v91
	v_fma_f32 v111, v102, v111, v116
	v_mul_f32_e32 v91, v105, v113
	v_mul_f32_e32 v116, v105, v112
	v_fma_f32 v112, v104, v112, -v91
	v_fma_f32 v113, v104, v113, v116
	v_mul_f32_e32 v91, v107, v115
	v_mul_f32_e32 v116, v107, v114
	v_fma_f32 v114, v106, v114, -v91
	v_fma_f32 v115, v106, v115, v116
	v_cvt_pk_bf16_f32 v120, v108, v109
	v_cvt_pk_bf16_f32 v121, v110, v111
	v_cvt_pk_bf16_f32 v122, v112, v113
	v_cvt_pk_bf16_f32 v123, v114, v115
	global_store_dwordx4 v89, v[120:123], s[16:17]
	s_add_u32 s16, s16, 0x14000
	s_addc_u32 s17, s17, 0
	v_mul_f32_e32 v91, v79, v108
	v_mul_f32_e32 v116, v79, v109
	v_cvt_pk_bf16_f32 v124, v91, v116
	v_mul_f32_e32 v91, v79, v110
	v_mul_f32_e32 v116, v79, v111
	v_cvt_pk_bf16_f32 v125, v91, v116
	v_mul_f32_e32 v91, v79, v112
	v_mul_f32_e32 v116, v79, v113
	v_cvt_pk_bf16_f32 v126, v91, v116
	v_mul_f32_e32 v91, v79, v114
	v_mul_f32_e32 v116, v79, v115
	v_cvt_pk_bf16_f32 v127, v91, v116
	ds_write_b128 v84, v[124:127] offset:1024
	v_mul_f32_e32 v91, v83, v108
	v_mul_f32_e32 v116, v83, v109
	v_cvt_pk_bf16_f32 v132, v91, v116
	v_mul_f32_e32 v91, v83, v110
	v_mul_f32_e32 v116, v83, v111
	v_cvt_pk_bf16_f32 v133, v91, v116
	v_mul_f32_e32 v91, v83, v112
	v_mul_f32_e32 v116, v83, v113
	v_cvt_pk_bf16_f32 v134, v91, v116
	v_mul_f32_e32 v91, v83, v114
	v_mul_f32_e32 v116, v83, v115
	v_cvt_pk_bf16_f32 v135, v91, v116
	ds_read_b64_tr_b16 v[120:121], v85
	ds_read_b64_tr_b16 v[122:123], v85 offset:256
	ds_read_b64_tr_b16 v[124:125], v86
	ds_read_b64_tr_b16 v[126:127], v86 offset:256
	s_waitcnt lgkmcnt(0)
	global_store_dwordx4 v87, v[120:123], s[36:37]
	global_store_dwordx4 v88, v[124:127], s[36:37]
	ds_write_b128 v84, v[128:131]
	ds_write_b128 v84, v[132:135] offset:1024
	s_nop 1
	ds_read_b64_tr_b16 v[120:121], v85
	ds_read_b64_tr_b16 v[122:123], v85 offset:256
	ds_read_b64_tr_b16 v[124:125], v86
	ds_read_b64_tr_b16 v[126:127], v86 offset:256
	s_waitcnt lgkmcnt(0)
	global_store_dwordx4 v87, v[120:123], s[40:41]
	global_store_dwordx4 v88, v[124:127], s[40:41]
	s_add_u32 s36, s36, 0xc0
	s_addc_u32 s37, s37, 0
	s_add_u32 s40, s40, 0xc0
	s_addc_u32 s41, s41, 0
	s_cmp_eq_u32 s48, 64
	s_cbranch_scc1 .Lsec1_b_done
	s_add_u32 s4, s4, s21
	s_addc_u32 s5, s5, 0
	global_load_dwordx4 v[100:103], v90, s[4:5]
	global_load_dwordx4 v[104:107], v90, s[4:5] offset:16
	s_waitcnt vmcnt(2)
	v_mul_f32_e32 v108, v246, v32
	v_mul_f32_e32 v109, v246, v33
	v_mul_f32_e32 v110, v246, v34
	v_mul_f32_e32 v111, v246, v35
	v_mul_f32_e32 v112, v246, v28
	v_mul_f32_e32 v113, v246, v29
	v_mul_f32_e32 v114, v246, v30
	v_mul_f32_e32 v115, v246, v31
	v_mul_f32_e32 v91, v93, v109
	v_mul_f32_e32 v116, v93, v108
	v_fma_f32 v108, v92, v108, -v91
	v_fma_f32 v109, v92, v109, v116
	v_mul_f32_e32 v91, v95, v111
	v_mul_f32_e32 v116, v95, v110
	v_fma_f32 v110, v94, v110, -v91
	v_fma_f32 v111, v94, v111, v116
	v_mul_f32_e32 v91, v97, v113
	v_mul_f32_e32 v116, v97, v112
	v_fma_f32 v112, v96, v112, -v91
	v_fma_f32 v113, v96, v113, v116
	v_mul_f32_e32 v91, v99, v115
	v_mul_f32_e32 v116, v99, v114
	v_fma_f32 v114, v98, v114, -v91
	v_fma_f32 v115, v98, v115, v116
	v_cvt_pk_bf16_f32 v120, v108, v109
	v_cvt_pk_bf16_f32 v121, v110, v111
	v_cvt_pk_bf16_f32 v122, v112, v113
	v_cvt_pk_bf16_f32 v123, v114, v115
	global_store_dwordx4 v89, v[120:123], s[16:17]
	s_add_u32 s16, s16, 0x4000
	s_addc_u32 s17, s17, 0
	v_mul_f32_e32 v91, v76, v108
	v_mul_f32_e32 v116, v76, v109
	v_cvt_pk_bf16_f32 v124, v91, v116
	v_mul_f32_e32 v91, v76, v110
	v_mul_f32_e32 v116, v76, v111
	v_cvt_pk_bf16_f32 v125, v91, v116
	v_mul_f32_e32 v91, v76, v112
	v_mul_f32_e32 v116, v76, v113
	v_cvt_pk_bf16_f32 v126, v91, v116
	v_mul_f32_e32 v91, v76, v114
	v_mul_f32_e32 v116, v76, v115
	v_cvt_pk_bf16_f32 v127, v91, v116
	ds_write_b128 v84, v[124:127]
	v_mul_f32_e32 v91, v80, v108
	v_mul_f32_e32 v116, v80, v109
	v_cvt_pk_bf16_f32 v128, v91, v116
	v_mul_f32_e32 v91, v80, v110
	v_mul_f32_e32 v116, v80, v111
	v_cvt_pk_bf16_f32 v129, v91, v116
	v_mul_f32_e32 v91, v80, v112
	v_mul_f32_e32 v116, v80, v113
	v_cvt_pk_bf16_f32 v130, v91, v116
	v_mul_f32_e32 v91, v80, v114
	v_mul_f32_e32 v116, v80, v115
	v_cvt_pk_bf16_f32 v131, v91, v116
	s_add_u32 s4, s4, s21
	s_addc_u32 s5, s5, 0
	global_load_dwordx4 v[92:95], v90, s[4:5]
	global_load_dwordx4 v[96:99], v90, s[4:5] offset:16
	s_waitcnt vmcnt(2)
	v_mul_f32_e32 v108, v247, v24
	v_mul_f32_e32 v109, v247, v25
	v_mul_f32_e32 v110, v247, v26
	v_mul_f32_e32 v111, v247, v27
	v_mul_f32_e32 v112, v247, v20
	v_mul_f32_e32 v113, v247, v21
	v_mul_f32_e32 v114, v247, v22
	v_mul_f32_e32 v115, v247, v23
	v_mul_f32_e32 v91, v101, v109
	v_mul_f32_e32 v116, v101, v108
	v_fma_f32 v108, v100, v108, -v91
	v_fma_f32 v109, v100, v109, v116
	v_mul_f32_e32 v91, v103, v111
	v_mul_f32_e32 v116, v103, v110
	v_fma_f32 v110, v102, v110, -v91
	v_fma_f32 v111, v102, v111, v116
	v_mul_f32_e32 v91, v105, v113
	v_mul_f32_e32 v116, v105, v112
	v_fma_f32 v112, v104, v112, -v91
	v_fma_f32 v113, v104, v113, v116
	v_mul_f32_e32 v91, v107, v115
	v_mul_f32_e32 v116, v107, v114
	v_fma_f32 v114, v106, v114, -v91
	v_fma_f32 v115, v106, v115, v116
	v_cvt_pk_bf16_f32 v120, v108, v109
	v_cvt_pk_bf16_f32 v121, v110, v111
	v_cvt_pk_bf16_f32 v122, v112, v113
	v_cvt_pk_bf16_f32 v123, v114, v115
	global_store_dwordx4 v89, v[120:123], s[16:17]
	s_add_u32 s16, s16, 0x4000
	s_addc_u32 s17, s17, 0
	v_mul_f32_e32 v91, v77, v108
	v_mul_f32_e32 v116, v77, v109
	v_cvt_pk_bf16_f32 v124, v91, v116
	v_mul_f32_e32 v91, v77, v110
	v_mul_f32_e32 v116, v77, v111
	v_cvt_pk_bf16_f32 v125, v91, v116
	v_mul_f32_e32 v91, v77, v112
	v_mul_f32_e32 v116, v77, v113
	v_cvt_pk_bf16_f32 v126, v91, v116
	v_mul_f32_e32 v91, v77, v114
	v_mul_f32_e32 v116, v77, v115
	v_cvt_pk_bf16_f32 v127, v91, v116
	ds_write_b128 v84, v[124:127] offset:1024
	v_mul_f32_e32 v91, v81, v108
	v_mul_f32_e32 v116, v81, v109
	v_cvt_pk_bf16_f32 v132, v91, v116
	v_mul_f32_e32 v91, v81, v110
	v_mul_f32_e32 v116, v81, v111
	v_cvt_pk_bf16_f32 v133, v91, v116
	v_mul_f32_e32 v91, v81, v112
	v_mul_f32_e32 v116, v81, v113
	v_cvt_pk_bf16_f32 v134, v91, v116
	v_mul_f32_e32 v91, v81, v114
	v_mul_f32_e32 v116, v81, v115
	v_cvt_pk_bf16_f32 v135, v91, v116
	ds_read_b64_tr_b16 v[120:121], v85
	ds_read_b64_tr_b16 v[122:123], v85 offset:256
	ds_read_b64_tr_b16 v[124:125], v86
	ds_read_b64_tr_b16 v[126:127], v86 offset:256
	s_waitcnt lgkmcnt(0)
	global_store_dwordx4 v87, v[120:123], s[36:37]
	global_store_dwordx4 v88, v[124:127], s[36:37]
	ds_write_b128 v84, v[128:131]
	ds_write_b128 v84, v[132:135] offset:1024
	s_nop 1
	ds_read_b64_tr_b16 v[120:121], v85
	ds_read_b64_tr_b16 v[122:123], v85 offset:256
	ds_read_b64_tr_b16 v[124:125], v86
	ds_read_b64_tr_b16 v[126:127], v86 offset:256
	s_waitcnt lgkmcnt(0)
	global_store_dwordx4 v87, v[120:123], s[40:41]
	global_store_dwordx4 v88, v[124:127], s[40:41]
	s_add_u32 s36, s36, 64
	s_addc_u32 s37, s37, 0
	s_add_u32 s40, s40, 64
	s_addc_u32 s41, s41, 0
	s_add_u32 s4, s4, s21
	s_addc_u32 s5, s5, 0
	global_load_dwordx4 v[100:103], v90, s[4:5]
	global_load_dwordx4 v[104:107], v90, s[4:5] offset:16
	s_waitcnt vmcnt(2)
	v_mul_f32_e32 v108, v248, v16
	v_mul_f32_e32 v109, v248, v17
	v_mul_f32_e32 v110, v248, v18
	v_mul_f32_e32 v111, v248, v19
	v_mul_f32_e32 v112, v248, v12
	v_mul_f32_e32 v113, v248, v13
	v_mul_f32_e32 v114, v248, v14
	v_mul_f32_e32 v115, v248, v15
	v_mul_f32_e32 v91, v93, v109
	v_mul_f32_e32 v116, v93, v108
	v_fma_f32 v108, v92, v108, -v91
	v_fma_f32 v109, v92, v109, v116
	v_mul_f32_e32 v91, v95, v111
	v_mul_f32_e32 v116, v95, v110
	v_fma_f32 v110, v94, v110, -v91
	v_fma_f32 v111, v94, v111, v116
	v_mul_f32_e32 v91, v97, v113
	v_mul_f32_e32 v116, v97, v112
	v_fma_f32 v112, v96, v112, -v91
	v_fma_f32 v113, v96, v113, v116
	v_mul_f32_e32 v91, v99, v115
	v_mul_f32_e32 v116, v99, v114
	v_fma_f32 v114, v98, v114, -v91
	v_fma_f32 v115, v98, v115, v116
	v_cvt_pk_bf16_f32 v120, v108, v109
	v_cvt_pk_bf16_f32 v121, v110, v111
	v_cvt_pk_bf16_f32 v122, v112, v113
	v_cvt_pk_bf16_f32 v123, v114, v115
	global_store_dwordx4 v89, v[120:123], s[16:17]
	s_add_u32 s16, s16, 0x4000
	s_addc_u32 s17, s17, 0
	v_mul_f32_e32 v91, v78, v108
	v_mul_f32_e32 v116, v78, v109
	v_cvt_pk_bf16_f32 v124, v91, v116
	v_mul_f32_e32 v91, v78, v110
	v_mul_f32_e32 v116, v78, v111
	v_cvt_pk_bf16_f32 v125, v91, v116
	v_mul_f32_e32 v91, v78, v112
	v_mul_f32_e32 v116, v78, v113
	v_cvt_pk_bf16_f32 v126, v91, v116
	v_mul_f32_e32 v91, v78, v114
	v_mul_f32_e32 v116, v78, v115
	v_cvt_pk_bf16_f32 v127, v91, v116
	ds_write_b128 v84, v[124:127]
	v_mul_f32_e32 v91, v82, v108
	v_mul_f32_e32 v116, v82, v109
	v_cvt_pk_bf16_f32 v128, v91, v116
	v_mul_f32_e32 v91, v82, v110
	v_mul_f32_e32 v116, v82, v111
	v_cvt_pk_bf16_f32 v129, v91, v116
	v_mul_f32_e32 v91, v82, v112
	v_mul_f32_e32 v116, v82, v113
	v_cvt_pk_bf16_f32 v130, v91, v116
	v_mul_f32_e32 v91, v82, v114
	v_mul_f32_e32 v116, v82, v115
	v_cvt_pk_bf16_f32 v131, v91, v116
	s_waitcnt vmcnt(0)
	v_mul_f32_e32 v108, v249, v8
	v_mul_f32_e32 v109, v249, v9
	v_mul_f32_e32 v110, v249, v10
	v_mul_f32_e32 v111, v249, v11
	v_mul_f32_e32 v112, v249, v4
	v_mul_f32_e32 v113, v249, v5
	v_mul_f32_e32 v114, v249, v6
	v_mul_f32_e32 v115, v249, v7
	v_mul_f32_e32 v91, v101, v109
	v_mul_f32_e32 v116, v101, v108
	v_fma_f32 v108, v100, v108, -v91
	v_fma_f32 v109, v100, v109, v116
	v_mul_f32_e32 v91, v103, v111
	v_mul_f32_e32 v116, v103, v110
	v_fma_f32 v110, v102, v110, -v91
	v_fma_f32 v111, v102, v111, v116
	v_mul_f32_e32 v91, v105, v113
	v_mul_f32_e32 v116, v105, v112
	v_fma_f32 v112, v104, v112, -v91
	v_fma_f32 v113, v104, v113, v116
	v_mul_f32_e32 v91, v107, v115
	v_mul_f32_e32 v116, v107, v114
	v_fma_f32 v114, v106, v114, -v91
	v_fma_f32 v115, v106, v115, v116
	v_cvt_pk_bf16_f32 v120, v108, v109
	v_cvt_pk_bf16_f32 v121, v110, v111
	v_cvt_pk_bf16_f32 v122, v112, v113
	v_cvt_pk_bf16_f32 v123, v114, v115
	global_store_dwordx4 v89, v[120:123], s[16:17]
	s_add_u32 s16, s16, 0x14000
	s_addc_u32 s17, s17, 0
	v_mul_f32_e32 v91, v79, v108
	v_mul_f32_e32 v116, v79, v109
	v_cvt_pk_bf16_f32 v124, v91, v116
	v_mul_f32_e32 v91, v79, v110
	v_mul_f32_e32 v116, v79, v111
	v_cvt_pk_bf16_f32 v125, v91, v116
	v_mul_f32_e32 v91, v79, v112
	v_mul_f32_e32 v116, v79, v113
	v_cvt_pk_bf16_f32 v126, v91, v116
	v_mul_f32_e32 v91, v79, v114
	v_mul_f32_e32 v116, v79, v115
	v_cvt_pk_bf16_f32 v127, v91, v116
	ds_write_b128 v84, v[124:127] offset:1024
	v_mul_f32_e32 v91, v83, v108
	v_mul_f32_e32 v116, v83, v109
	v_cvt_pk_bf16_f32 v132, v91, v116
	v_mul_f32_e32 v91, v83, v110
	v_mul_f32_e32 v116, v83, v111
	v_cvt_pk_bf16_f32 v133, v91, v116
	v_mul_f32_e32 v91, v83, v112
	v_mul_f32_e32 v116, v83, v113
	v_cvt_pk_bf16_f32 v134, v91, v116
	v_mul_f32_e32 v91, v83, v114
	v_mul_f32_e32 v116, v83, v115
	v_cvt_pk_bf16_f32 v135, v91, v116
	ds_read_b64_tr_b16 v[120:121], v85
	ds_read_b64_tr_b16 v[122:123], v85 offset:256
	ds_read_b64_tr_b16 v[124:125], v86
	ds_read_b64_tr_b16 v[126:127], v86 offset:256
	s_waitcnt lgkmcnt(0)
	global_store_dwordx4 v87, v[120:123], s[36:37]
	global_store_dwordx4 v88, v[124:127], s[36:37]
	ds_write_b128 v84, v[128:131]
	ds_write_b128 v84, v[132:135] offset:1024
	s_nop 1
	ds_read_b64_tr_b16 v[120:121], v85
	ds_read_b64_tr_b16 v[122:123], v85 offset:256
	ds_read_b64_tr_b16 v[124:125], v86
	ds_read_b64_tr_b16 v[126:127], v86 offset:256
	s_waitcnt lgkmcnt(0)
	global_store_dwordx4 v87, v[120:123], s[40:41]
	global_store_dwordx4 v88, v[124:127], s[40:41]
